# grid barrier: globally-last XCC leader bumps all per-XCC generation words (release path one hop shorter), on v27
# speedup vs baseline: 1.0040x; 1.0040x over previous
.LBB0_735:
	s_or_b64 exec, exec, s[6:7]
	s_mov_b64 s[6:7], exec
	v_mbcnt_lo_u32_b32 v0, s6, 0
	v_mbcnt_hi_u32_b32 v0, s7, v0
	v_cmp_eq_u32_e32 vcc, 0, v0
	s_waitcnt vmcnt(0)
	buffer_inv sc1
	s_and_saveexec_b64 s[10:11], vcc
	s_branch .LBB0_737
	s_bcnt1_i32_b64 s2, s[6:7]
	v_mov_b32_e32 v0, s2
	v_mov_b32_e32 v1, 0x2000
	global_atomic_add v1, v0, s[8:9] offset:1024

.Lgb_last:
	s_or_b64 exec, exec, s[12:13]
	global_atomic_add v[0:1], v159, off
	s_mov_b32 s14, 0xffffef00
	s_mov_b32 s15, -1
	v_lshl_add_u64 v[2:3], v[0:1], 0, s[14:15]
	global_atomic_add v[2:3], v159, off
	global_atomic_add v[2:3], v159, off offset:256
	global_atomic_add v[2:3], v159, off offset:512
	global_atomic_add v[2:3], v159, off offset:768
	global_atomic_add v[2:3], v159, off offset:1024
	global_atomic_add v[2:3], v159, off offset:1280
	global_atomic_add v[2:3], v159, off offset:1536
	global_atomic_add v[2:3], v159, off offset:1792
	global_atomic_add v[2:3], v159, off offset:2048
	global_atomic_add v[2:3], v159, off offset:2304
	global_atomic_add v[2:3], v159, off offset:2560
	global_atomic_add v[2:3], v159, off offset:2816
	global_atomic_add v[2:3], v159, off offset:3072
	global_atomic_add v[2:3], v159, off offset:3328
	global_atomic_add v[2:3], v159, off offset:3584
	global_atomic_add v[2:3], v159, off offset:3840
	s_mov_b64 s[6:7], exec
	s_branch .LBB0_735
